# norm phases: gain vectors loaded once before the row loop (no per-row load/wait/store ladder) and the 6-step ds_bpermute wave reduction replaced by DPP adds + v_readlane
# speedup vs baseline: 1.0456x; 1.0045x over previous
; DI float4 ldgf4(const void* p) { const f32x4v v = *(const GAS f32x4v*)p; return make_float4(v.x, v.y, v.z, v.w); }
; DI void phase_final(const Params& p, int tid) {
;   const int lane = tid & 63;
;   const int gw = blockIdx.x * 4 + (tid >> 6), nw = gridDim.x * 4;
;   for (int g = gw; g < MPAD; g += nw) {
;     if (((g >> 7) == 0) || ((g >> 7) == 129) || ((g >> 7) >= 258 && ((g >> 7) - 258) % 65 == 0)) continue;
;     float* xr = xrow_dst(p, g);
;     float4 v[4];
; #pragma unroll
;     for (int q = 0; q < 4; ++q) v[q] = ldgf4((const float4*)xr + lane + 64 * q);
;     float ss = 0.f;
; #pragma unroll
;     for (int q = 0; q < 4; ++q) ss += v[q].x * v[q].x + v[q].y * v[q].y + v[q].z * v[q].z + v[q].w * v[q].w;
; #pragma unroll
;     for (int o = 32; o >= 1; o >>= 1) ss += __shfl_xor(ss, o);
;     const float rstd = rsqrtf(ss * (1.0f / 1024.0f) + EPS);
; #pragma unroll
;     for (int q = 0; q < 4; ++q) {
;       const float4 gg = ldgf4((const float4*)p.fin_g + lane + 64 * q);
;       float4 o = make_float4(v[q].x * rstd * gg.x, v[q].y * rstd * gg.y, v[q].z * rstd * gg.z, v[q].w * rstd * gg.w);
;       stgf4((float4*)xr + lane + 64 * q, o);
;     }
;   }
.LBB0_85:
	v_readlane_b32 s0, v253, 14
	v_readlane_b32 s40, v253, 30
	v_readlane_b32 s2, v253, 16
	v_readlane_b32 s3, v253, 17
	v_readlane_b32 s6, v253, 20
	v_readlane_b32 s7, v253, 21
	v_readlane_b32 s10, v253, 24
	v_readlane_b32 s11, v253, 25
	v_readlane_b32 s14, v253, 28
	v_readlane_b32 s15, v253, 29
	v_readlane_b32 s41, v253, 31
	v_readlane_b32 s42, v253, 32
	v_readlane_b32 s43, v253, 33
	v_readlane_b32 s1, v253, 15
	v_readlane_b32 s4, v253, 18
	v_readlane_b32 s5, v253, 19
	v_readlane_b32 s8, v253, 22
	v_readlane_b32 s9, v253, 23
	v_readlane_b32 s12, v253, 26
	v_readlane_b32 s13, v253, 27
	s_mov_b64 s[70:71], s[14:15]
	s_mov_b64 s[16:17], s[42:43]
	s_mov_b64 s[20:21], s[2:3]
	s_mov_b64 s[14:15], s[40:41]
	s_mov_b64 s[2:3], s[6:7]
	s_mov_b64 s[24:25], s[10:11]
	v_readlane_b32 s44, v253, 34
	v_writelane_b32 v254, s16, 15
	v_readlane_b32 s45, v253, 35
	v_readlane_b32 s46, v253, 36
	v_writelane_b32 v254, s17, 16
	v_writelane_b32 v254, s14, 17
	v_readlane_b32 s47, v253, 37
	v_readlane_b32 s48, v253, 38
	v_writelane_b32 v254, s15, 18
	v_writelane_b32 v254, s12, 19
	v_readlane_b32 s49, v253, 39
	v_readlane_b32 s50, v253, 40
	v_writelane_b32 v254, s13, 20
	v_writelane_b32 v254, s8, 21
	v_readlane_b32 s51, v253, 41
	v_readlane_b32 s52, v253, 42
	v_writelane_b32 v254, s9, 22
	v_writelane_b32 v254, s2, 23
	v_readlane_b32 s53, v253, 43
	v_readlane_b32 s54, v253, 44
	v_writelane_b32 v254, s3, 24
	v_writelane_b32 v254, s4, 25
	v_readlane_b32 s55, v253, 45
	s_mov_b64 s[28:29], s[46:47]
	v_writelane_b32 v254, s5, 26
	v_writelane_b32 v254, s0, 27
	s_mov_b64 s[10:11], s[54:55]
	s_mov_b64 s[40:41], s[44:45]
	v_writelane_b32 v254, s1, 28
	v_readlane_b32 s0, v253, 4
	v_readlane_b32 s1, v253, 5
	v_readlane_b32 s2, v253, 6
	v_readlane_b32 s3, v253, 7
	v_readlane_b32 s4, v253, 8
	v_readlane_b32 s5, v253, 9
	v_readlane_b32 s6, v253, 10
	v_readlane_b32 s7, v253, 11
	s_mov_b64 s[8:9], s[0:1]
	s_mov_b64 s[26:27], s[4:5]
	s_mov_b64 s[4:5], s[50:51]
	s_mov_b64 s[0:1], s[2:3]
	s_mov_b64 s[86:87], s[48:49]
	s_mov_b64 s[68:69], s[6:7]
	s_mov_b64 s[2:3], s[52:53]
	s_xor_b64 s[38:39], s[30:31], -1
	v_writelane_b32 v254, s10, 29
	v_mov_b32_e32 v245, v193
	s_mov_b64 s[6:7], 0
	v_writelane_b32 v254, s11, 30
	v_writelane_b32 v254, s4, 31
	s_movk_i32 s18, 0xffbf
	s_mov_b32 s19, 0x102ff
	v_writelane_b32 v254, s5, 32
	v_writelane_b32 v254, s8, 33
	s_mov_b64 s[4:5], 0
	s_nop 0
	v_writelane_b32 v254, s9, 34
	s_mov_b64 s[8:9], -1
	v_readlane_b32 s23, v254, 10
	s_cmp_lt_i32 s23, 21
	s_cbranch_scc1 .LBB0_109
	s_cmp_eq_u32 s23, 21
	s_mov_b64 s[6:7], -1
	s_cbranch_scc0 .LBB0_108
	v_ashrrev_i32_e32 v0, 6, v245
	v_add_u32_e32 v25, s64, v0
	v_cmp_gt_i32_e32 vcc, s93, v25
	s_and_saveexec_b64 s[6:7], vcc
	s_cbranch_execz .LBB0_107
	v_and_b32_e32 v0, 63, v245
	s_add_u32 s8, s68, 0x2e20800
	v_lshlrev_b32_e32 v128, 4, v0
	s_addc_u32 s9, s69, 0
	v_lshl_add_u64 v[20:21], s[0:1], 0, v[128:129]
	s_mov_b64 s[10:11], 0
	v_lshlrev_b32_e32 v128, 4, v0
	global_load_dwordx4 v[36:39], v[20:21], off
	global_load_dwordx4 v[40:43], v[20:21], off offset:1024
	global_load_dwordx4 v[44:47], v[20:21], off offset:2048
	global_load_dwordx4 v[48:51], v[20:21], off offset:3072
	s_branch .LBB0_91
.LBB0_89:
	s_or_b64 exec, exec, s[12:13]
	v_lshl_add_u64 v[22:23], v[0:1], 0, v[128:129]
	global_load_dwordx4 v[12:15], v[22:23], off
	global_load_dwordx4 v[8:11], v[22:23], off offset:1024
	global_load_dwordx4 v[4:7], v[22:23], off offset:2048
	global_load_dwordx4 v[0:3], v[22:23], off offset:3072
	v_cmp_lt_i32_e32 vcc, v229, v228
	s_mov_b32 s12, 0x800000
	s_waitcnt vmcnt(0)
	v_mov_b32_e32 v18, v13
	s_waitcnt vmcnt(2)
	v_mov_b32_e32 v19, v9
	v_mov_b32_e32 v16, v12
	v_mov_b32_e32 v17, v8
	v_pk_mul_f32 v[18:19], v[18:19], v[18:19]
	s_waitcnt vmcnt(1)
	v_mov_b32_e32 v26, v5
	v_pk_fma_f32 v[16:17], v[16:17], v[16:17], v[18:19]
	v_mov_b32_e32 v18, v14
	v_mov_b32_e32 v19, v10
	v_pk_fma_f32 v[16:17], v[18:19], v[18:19], v[16:17]
	v_mov_b32_e32 v18, v15
	v_mov_b32_e32 v19, v11
	s_waitcnt vmcnt(0)
	v_mov_b32_e32 v27, v1
	v_pk_fma_f32 v[16:17], v[18:19], v[18:19], v[16:17]
	v_mov_b32_e32 v18, v4
	v_mov_b32_e32 v19, v0
	v_pk_mul_f32 v[26:27], v[26:27], v[26:27]
	v_add_f32_e32 v16, v16, v17
	v_pk_fma_f32 v[18:19], v[18:19], v[18:19], v[26:27]
	v_mov_b32_e32 v26, v6
	v_mov_b32_e32 v27, v2
	v_pk_fma_f32 v[18:19], v[26:27], v[26:27], v[18:19]
	v_mov_b32_e32 v26, v7
	v_mov_b32_e32 v27, v3
	v_pk_fma_f32 v[18:19], v[26:27], v[26:27], v[18:19]
	v_cndmask_b32_e32 v17, v227, v229, vcc
	v_add_f32_e32 v16, v16, v18
	v_add_f32_e32 v16, v16, v19
	v_lshlrev_b32_e32 v17, 2, v17
	s_nop 1
	v_add_f32_dpp v16, v16, v16 quad_perm:[1,0,3,2] row_mask:0xf bank_mask:0xf
	s_nop 1
	v_add_f32_dpp v16, v16, v16 quad_perm:[2,3,0,1] row_mask:0xf bank_mask:0xf
	s_nop 1
	v_add_f32_dpp v16, v16, v16 row_half_mirror row_mask:0xf bank_mask:0xf
	s_nop 1
	v_add_f32_dpp v16, v16, v16 row_mirror row_mask:0xf bank_mask:0xf
	s_nop 1
	v_add_f32_dpp v16, v16, v16 row_bcast:15 row_mask:0xa bank_mask:0xf
	s_nop 1
	v_add_f32_dpp v16, v16, v16 row_bcast:31 row_mask:0xc bank_mask:0xf
	s_nop 1
	v_readlane_b32 vcc_lo, v16, 63
	s_nop 3
	v_mov_b32_e32 v16, vcc_lo
	v_fmamk_f32 v16, v16, 0x3a800000, v224
	v_cmp_gt_f32_e32 vcc, s12, v16
	v_mul_f32_e32 v17, 0x4b800000, v16
	s_nop 0
	v_cndmask_b32_e32 v16, v16, v17, vcc
	v_rsq_f32_e32 v16, v16
	s_nop 0
	v_mul_f32_e32 v17, 0x45800000, v16
	v_cndmask_b32_e32 v24, v16, v17, vcc
	v_pk_mul_f32 v[12:13], v[12:13], v[24:25] op_sel_hi:[1,0]
	v_pk_mul_f32 v[14:15], v[14:15], v[24:25] op_sel_hi:[1,0]
	v_pk_mul_f32 v[10:11], v[10:11], v[24:25] op_sel_hi:[1,0]
	v_pk_mul_f32 v[8:9], v[8:9], v[24:25] op_sel_hi:[1,0]
	v_pk_mul_f32 v[6:7], v[6:7], v[24:25] op_sel_hi:[1,0]
	v_pk_mul_f32 v[4:5], v[4:5], v[24:25] op_sel_hi:[1,0]
	v_pk_mul_f32 v[2:3], v[2:3], v[24:25] op_sel_hi:[1,0]
	v_pk_mul_f32 v[0:1], v[0:1], v[24:25] op_sel_hi:[1,0]
	v_pk_mul_f32 v[14:15], v[38:39], v[14:15]
	v_pk_mul_f32 v[12:13], v[36:37], v[12:13]
	global_store_dwordx4 v[22:23], v[12:15], off
	v_pk_mul_f32 v[8:9], v[40:41], v[8:9]
	v_pk_mul_f32 v[10:11], v[42:43], v[10:11]
	global_store_dwordx4 v[22:23], v[8:11], off offset:1024
	v_pk_mul_f32 v[4:5], v[44:45], v[4:5]
	v_pk_mul_f32 v[6:7], v[46:47], v[6:7]
	global_store_dwordx4 v[22:23], v[4:7], off offset:2048
	v_pk_mul_f32 v[0:1], v[48:49], v[0:1]
	v_pk_mul_f32 v[2:3], v[50:51], v[2:3]
	global_store_dwordx4 v[22:23], v[0:3], off offset:3072

; DI void phase_norm(const Params& p, const float* __restrict__ gain, bool from_input, bool zero_ssq, int tid) {
;   const int lane = tid & 63;
;   const int gw = blockIdx.x * 4 + (tid >> 6), nw = gridDim.x * 4;
;   u16* HN = (u16*)(p.ws + OFF_HN);
;   float* ssq = (float*)(p.ws + OFF_SSQ);
;   for (int g = gw; g < MPAD; g += nw) {
;     const float* xr = xrow_src(p, g, from_input);
;     u16* hr = HN + (size_t)g * 1024;
; __global__ void __launch_bounds__(256, 2) mega(Params pin) {
;     ...
;     } else if (sub == 5) {
;       phase_norm(p, p.mlp_g + layer * 1024, false, false, tid);
.LBB0_131:
	s_cmp_gt_i32 s20, 4
	s_mov_b64 s[0:1], -1
	s_cbranch_scc0 .LBB0_152
	v_ashrrev_i32_e32 v0, 6, v245
	v_add_u32_e32 v16, s64, v0
	v_cmp_gt_i32_e32 vcc, s93, v16
	s_and_saveexec_b64 s[0:1], vcc
	v_readlane_b32 s12, v254, 8
	v_readlane_b32 s13, v254, 9
	s_cbranch_execz .LBB0_151
	s_lshl_b32 s4, s53, 10
	s_ashr_i32 s5, s4, 31
	s_lshl_b64 s[4:5], s[4:5], 2
	s_add_u32 s2, s2, s4
	v_and_b32_e32 v0, 63, v245
	s_addc_u32 s3, s3, s5
	v_lshlrev_b32_e32 v128, 4, v0
	v_ashrrev_i32_e32 v17, 31, v16
	v_lshl_add_u64 v[18:19], s[2:3], 0, v[128:129]
	s_add_u32 s2, s68, 0x2e20800
	v_lshlrev_b64 v[2:3], 11, v[16:17]
	s_addc_u32 s3, s69, 0
	v_lshlrev_b32_e32 v20, 5, v0
	v_mov_b32_e32 v21, v129
	v_lshl_add_u64 v[22:23], s[68:69], 0, v[2:3]
	v_lshlrev_b32_e32 v24, 3, v0
	v_mov_b32_e32 v25, v129
	s_mov_b64 s[4:5], 0
	v_lshlrev_b32_e32 v26, 4, v0
	global_load_dwordx4 v[36:39], v[18:19], off
	global_load_dwordx4 v[40:43], v[18:19], off offset:1024
	global_load_dwordx4 v[44:47], v[18:19], off offset:2048
	global_load_dwordx4 v[48:51], v[18:19], off offset:3072
	s_branch .LBB0_135

; DI float4 ldgf4(const void* p) { const f32x4v v = *(const GAS f32x4v*)p; return make_float4(v.x, v.y, v.z, v.w); }
; DI void store4g(u16* dst, float a, float b, float c, float d) { u32x2 v = {pack2(a, b), pack2(c, d)}; stg8(dst, v); }
; DI void phase_norm(const Params& p, const float* __restrict__ gain, bool from_input, bool zero_ssq, int tid) {
;     ...
;   for (int g = gw; g < MPAD; g += nw) {
;     const float* xr = xrow_src(p, g, from_input);
;     u16* hr = HN + (size_t)g * 1024;
;     if (!xr) {
;       u32x4 z = {0u, 0u, 0u, 0u};
;       *(u32x4*)(hr + lane * 16) = z;
;       *(u32x4*)(hr + lane * 16 + 8) = z;
;     } else {
;       float4 v[4];
; #pragma unroll
;       for (int q = 0; q < 4; ++q) v[q] = ldgf4((const float4*)xr + lane + 64 * q);
;       float ss = 0.f;
; #pragma unroll
;       for (int q = 0; q < 4; ++q) ss += v[q].x * v[q].x + v[q].y * v[q].y + v[q].z * v[q].z + v[q].w * v[q].w;
; #pragma unroll
;       for (int o = 32; o >= 1; o >>= 1) ss += __shfl_xor(ss, o);
;       const float rstd = rsqrtf(ss * (1.0f / 1024.0f) + EPS);
; #pragma unroll
;       for (int q = 0; q < 4; ++q) {
;         const float4 gg = ldgf4((const float4*)gain + lane + 64 * q);
;         store4g(hr + 4 * (lane + 64 * q), v[q].x * rstd * gg.x, v[q].y * rstd * gg.y, v[q].z * rstd * gg.z, v[q].w * rstd * gg.w);
;       }
;     }
.LBB0_145:
	s_andn2_saveexec_b64 s[6:7], s[6:7]
	v_subrev_co_u32_e32 v0, vcc, 0x70, v3
	v_lshl_add_u32 v128, v4, 4, v0
	v_lshlrev_b64 v[0:1], 12, v[128:129]
	v_lshl_add_u64 v[0:1], s[2:3], 0, v[0:1]
	v_cndmask_b32_e64 v1, v1, 0, vcc
	v_cndmask_b32_e64 v0, v0, 0, vcc
	s_or_b64 exec, exec, s[6:7]
	v_cmp_ne_u64_e32 vcc, 0, v[0:1]
	s_and_saveexec_b64 s[6:7], vcc
	s_xor_b64 s[6:7], exec, s[6:7]
	s_cbranch_execz .LBB0_149
	v_mov_b32_e32 v27, v129
	v_lshl_add_u64 v[0:1], v[0:1], 0, v[26:27]
	global_load_dwordx4 v[12:15], v[0:1], off
	global_load_dwordx4 v[8:11], v[0:1], off offset:1024
	global_load_dwordx4 v[4:7], v[0:1], off offset:2048
	s_nop 0
	global_load_dwordx4 v[0:3], v[0:1], off offset:3072
	v_cmp_lt_i32_e32 vcc, v229, v228
	s_mov_b32 s8, 0x800000
	s_waitcnt lgkmcnt(0)
	v_lshl_add_u64 v[34:35], v[22:23], 0, v[24:25]
	v_cndmask_b32_e32 v27, v227, v229, vcc
	v_lshlrev_b32_e32 v27, 2, v27
	v_cmp_lt_i32_e32 vcc, v230, v228
	s_waitcnt vmcnt(0)
	v_mov_b32_e32 v30, v13
	s_waitcnt vmcnt(2)
	v_mov_b32_e32 v31, v9
	v_mov_b32_e32 v28, v12
	v_mov_b32_e32 v29, v8
	v_pk_mul_f32 v[30:31], v[30:31], v[30:31]
	s_waitcnt vmcnt(1)
	v_mov_b32_e32 v32, v5
	v_pk_fma_f32 v[28:29], v[28:29], v[28:29], v[30:31]
	v_mov_b32_e32 v30, v14
	v_mov_b32_e32 v31, v10
	v_pk_fma_f32 v[28:29], v[30:31], v[30:31], v[28:29]
	v_mov_b32_e32 v30, v15
	v_mov_b32_e32 v31, v11
	s_waitcnt vmcnt(0)
	v_mov_b32_e32 v33, v1
	v_pk_fma_f32 v[28:29], v[30:31], v[30:31], v[28:29]
	v_mov_b32_e32 v30, v4
	v_mov_b32_e32 v31, v0
	v_pk_mul_f32 v[32:33], v[32:33], v[32:33]
	v_add_f32_e32 v17, v28, v29
	v_pk_fma_f32 v[30:31], v[30:31], v[30:31], v[32:33]
	v_mov_b32_e32 v32, v6
	v_mov_b32_e32 v33, v2
	v_pk_fma_f32 v[30:31], v[32:33], v[32:33], v[30:31]
	v_mov_b32_e32 v32, v7
	v_mov_b32_e32 v33, v3
	v_pk_fma_f32 v[30:31], v[32:33], v[32:33], v[30:31]
	s_nop 0
	v_add_f32_e32 v17, v17, v30
	v_add_f32_e32 v17, v17, v31
	s_nop 1
	v_add_f32_dpp v17, v17, v17 quad_perm:[1,0,3,2] row_mask:0xf bank_mask:0xf
	s_nop 1
	v_add_f32_dpp v17, v17, v17 quad_perm:[2,3,0,1] row_mask:0xf bank_mask:0xf
	s_nop 1
	v_add_f32_dpp v17, v17, v17 row_half_mirror row_mask:0xf bank_mask:0xf
	s_nop 1
	v_add_f32_dpp v17, v17, v17 row_mirror row_mask:0xf bank_mask:0xf
	s_nop 1
	v_add_f32_dpp v17, v17, v17 row_bcast:15 row_mask:0xa bank_mask:0xf
	s_nop 1
	v_add_f32_dpp v17, v17, v17 row_bcast:31 row_mask:0xc bank_mask:0xf
	s_nop 1
	v_readlane_b32 vcc_lo, v17, 63
	s_nop 3
	v_mov_b32_e32 v17, vcc_lo
	v_fmamk_f32 v17, v17, 0x3a800000, v224
	v_cmp_gt_f32_e32 vcc, s8, v17
	v_mul_f32_e32 v27, 0x4b800000, v17
	s_nop 0
	v_cndmask_b32_e32 v17, v17, v27, vcc
	v_rsq_f32_e32 v17, v17
	s_nop 0
	v_mul_f32_e32 v27, 0x45800000, v17
	v_cndmask_b32_e32 v28, v17, v27, vcc
	v_pk_mul_f32 v[12:13], v[12:13], v[28:29] op_sel_hi:[1,0]
	v_pk_mul_f32 v[14:15], v[14:15], v[28:29] op_sel_hi:[1,0]
	v_pk_mul_f32 v[8:9], v[8:9], v[28:29] op_sel_hi:[1,0]
	v_pk_mul_f32 v[10:11], v[10:11], v[28:29] op_sel_hi:[1,0]
	v_pk_mul_f32 v[4:5], v[4:5], v[28:29] op_sel_hi:[1,0]
	v_pk_mul_f32 v[6:7], v[6:7], v[28:29] op_sel_hi:[1,0]
	v_pk_mul_f32 v[0:1], v[0:1], v[28:29] op_sel_hi:[1,0]
	v_pk_mul_f32 v[2:3], v[2:3], v[28:29] op_sel_hi:[1,0]
	v_pk_mul_f32 v[12:13], v[36:37], v[12:13]
	v_pk_mul_f32 v[14:15], v[38:39], v[14:15]
	v_add_co_u32_e32 v30, vcc, s16, v34
	v_cvt_pk_bf16_f32 v12, v12, v13
	v_cvt_pk_bf16_f32 v13, v14, v15
	v_addc_co_u32_e32 v31, vcc, 0, v35, vcc
	global_store_dwordx2 v[30:31], v[12:13], off offset:3072
	v_pk_mul_f32 v[8:9], v[40:41], v[8:9]
	v_pk_mul_f32 v[10:11], v[42:43], v[10:11]
	v_cvt_pk_bf16_f32 v8, v8, v9
	v_cvt_pk_bf16_f32 v9, v10, v11
	global_store_dwordx2 v[30:31], v[8:9], off offset:3584
	v_pk_mul_f32 v[4:5], v[44:45], v[4:5]
	v_pk_mul_f32 v[6:7], v[46:47], v[6:7]
	v_add_co_u32_e32 v8, vcc, s17, v34
	v_cvt_pk_bf16_f32 v4, v4, v5
	v_cvt_pk_bf16_f32 v5, v6, v7
	v_addc_co_u32_e32 v9, vcc, 0, v35, vcc
	global_store_dwordx2 v[8:9], v[4:5], off
	v_pk_mul_f32 v[0:1], v[48:49], v[0:1]
	v_pk_mul_f32 v[2:3], v[50:51], v[2:3]
	v_cvt_pk_bf16_f32 v0, v0, v1
	v_cvt_pk_bf16_f32 v1, v2, v3
	global_store_dwordx2 v[8:9], v[0:1], off offset:512

; DI void phase_norm(const Params& p, const float* __restrict__ gain, bool from_input, bool zero_ssq, int tid) {
;   const int lane = tid & 63;
;   const int gw = blockIdx.x * 4 + (tid >> 6), nw = gridDim.x * 4;
;   u16* HN = (u16*)(p.ws + OFF_HN);
;   float* ssq = (float*)(p.ws + OFF_SSQ);
;   for (int g = gw; g < MPAD; g += nw) {
;     const float* xr = xrow_src(p, g, from_input);
;     u16* hr = HN + (size_t)g * 1024;
; __global__ void __launch_bounds__(256, 2) mega(Params pin) {
;     ...
;     if (sub == 0) {
;       phase_norm(p, p.attn_g + layer * 1024, layer == 0, true, tid);
.LBB0_433:
	v_readlane_b32 s16, v253, 61
	v_readlane_b32 s30, v254, 35
	s_andn2_b64 vcc, exec, s[42:43]
	v_readlane_b32 s17, v253, 62
	s_movk_i32 s18, 0xffbf
	s_mov_b32 s19, 0x102ff
	s_mov_b32 s20, 0x2f87000
	s_mov_b32 s21, 0x2f88000
	v_readlane_b32 s31, v254, 36
	v_readlane_b32 s23, v254, 10
	s_cbranch_vccnz .LBB0_468
	v_ashrrev_i32_e32 v0, 6, v245
	v_add_u32_e32 v16, s64, v0
	v_cmp_gt_i32_e32 vcc, s93, v16
	s_and_saveexec_b64 s[0:1], vcc
	v_readlane_b32 s26, v254, 25
	v_readlane_b32 s36, v254, 37
	v_readlane_b32 s27, v254, 26
	v_readlane_b32 s37, v254, 38
	s_cbranch_execz .LBB0_467
	s_add_i32 s2, s23, 8
	s_cmp_gt_u32 s2, 18
	s_cselect_b64 s[2:3], -1, 0
	s_lshl_b32 s4, s53, 10
	s_ashr_i32 s5, s4, 31
	s_lshl_b64 s[4:5], s[4:5], 2
	v_readlane_b32 s6, v254, 23
	v_readlane_b32 s7, v254, 24
	s_add_u32 s4, s6, s4
	v_and_b32_e32 v0, 63, v245
	s_addc_u32 s5, s7, s5
	v_lshlrev_b32_e32 v128, 4, v0
	v_mul_u32_u24_e32 v1, 0x10300, v0
	v_lshl_add_u64 v[18:19], s[4:5], 0, v[128:129]
	v_ashrrev_i32_e32 v17, 31, v16
	v_lshlrev_b32_e32 v128, 2, v1
	s_add_u32 s6, s68, 0x2e20800
	v_lshl_add_u64 v[2:3], v[16:17], 2, v[128:129]
	s_mov_b64 s[8:9], 0x2e80800
	v_lshlrev_b64 v[22:23], 11, v[16:17]
	v_cmp_gt_u32_e64 s[4:5], 4, v0
	s_addc_u32 s7, s69, 0
	v_lshl_add_u64 v[20:21], v[2:3], 0, s[8:9]
	v_lshl_or_b32 v24, v0, 5, v22
	v_mov_b32_e32 v25, v23
	v_lshl_or_b32 v22, v0, 3, v22
	s_mov_b64 s[8:9], 0
	v_lshlrev_b32_e32 v26, 4, v0
	global_load_dwordx4 v[36:39], v[18:19], off
	global_load_dwordx4 v[40:43], v[18:19], off offset:1024
	global_load_dwordx4 v[44:47], v[18:19], off offset:2048
	global_load_dwordx4 v[48:51], v[18:19], off offset:3072
	s_branch .LBB0_437

; DI float4 ldgf4(const void* p) { const f32x4v v = *(const GAS f32x4v*)p; return make_float4(v.x, v.y, v.z, v.w); }
; DI void store4g(u16* dst, float a, float b, float c, float d) { u32x2 v = {pack2(a, b), pack2(c, d)}; stg8(dst, v); }
; DI void phase_norm(const Params& p, const float* __restrict__ gain, bool from_input, bool zero_ssq, int tid) {
;     ...
;   for (int g = gw; g < MPAD; g += nw) {
;     const float* xr = xrow_src(p, g, from_input);
;     u16* hr = HN + (size_t)g * 1024;
;     if (!xr) {
;       u32x4 z = {0u, 0u, 0u, 0u};
;       *(u32x4*)(hr + lane * 16) = z;
;       *(u32x4*)(hr + lane * 16 + 8) = z;
;     } else {
;       float4 v[4];
; #pragma unroll
;       for (int q = 0; q < 4; ++q) v[q] = ldgf4((const float4*)xr + lane + 64 * q);
;       float ss = 0.f;
; #pragma unroll
;       for (int q = 0; q < 4; ++q) ss += v[q].x * v[q].x + v[q].y * v[q].y + v[q].z * v[q].z + v[q].w * v[q].w;
; #pragma unroll
;       for (int o = 32; o >= 1; o >>= 1) ss += __shfl_xor(ss, o);
;       const float rstd = rsqrtf(ss * (1.0f / 1024.0f) + EPS);
; #pragma unroll
;       for (int q = 0; q < 4; ++q) {
;         const float4 gg = ldgf4((const float4*)gain + lane + 64 * q);
;         store4g(hr + 4 * (lane + 64 * q), v[q].x * rstd * gg.x, v[q].y * rstd * gg.y, v[q].z * rstd * gg.z, v[q].w * rstd * gg.w);
;       }
;     }
.LBB0_461:
	s_or_b64 exec, exec, s[10:11]
	v_cmp_ne_u64_e32 vcc, 0, v[0:1]
	s_and_saveexec_b64 s[10:11], vcc
	s_xor_b64 s[10:11], exec, s[10:11]
	s_cbranch_execz .LBB0_464
	v_mov_b32_e32 v27, v129
	v_lshl_add_u64 v[0:1], v[0:1], 0, v[26:27]
	global_load_dwordx4 v[12:15], v[0:1], off
	global_load_dwordx4 v[8:11], v[0:1], off offset:1024
	global_load_dwordx4 v[4:7], v[0:1], off offset:2048
	s_nop 0
	global_load_dwordx4 v[0:3], v[0:1], off offset:3072
	v_cmp_lt_i32_e32 vcc, v229, v228
	s_mov_b32 s12, 0x800000
	s_waitcnt lgkmcnt(0)
	v_lshl_add_u64 v[34:35], s[68:69], 0, v[22:23]
	v_cndmask_b32_e32 v27, v227, v229, vcc
	v_lshlrev_b32_e32 v27, 2, v27
	v_cmp_lt_i32_e32 vcc, v230, v228
	s_waitcnt vmcnt(0)
	v_mov_b32_e32 v30, v13
	v_mov_b32_e32 v31, v9
	v_mov_b32_e32 v28, v12
	v_mov_b32_e32 v29, v8
	v_pk_mul_f32 v[30:31], v[30:31], v[30:31]
	v_mov_b32_e32 v32, v5
	v_pk_fma_f32 v[28:29], v[28:29], v[28:29], v[30:31]
	v_mov_b32_e32 v30, v14
	v_mov_b32_e32 v31, v10
	v_pk_fma_f32 v[28:29], v[30:31], v[30:31], v[28:29]
	v_mov_b32_e32 v30, v15
	v_mov_b32_e32 v31, v11
	v_mov_b32_e32 v33, v1
	v_pk_fma_f32 v[28:29], v[30:31], v[30:31], v[28:29]
	v_mov_b32_e32 v30, v4
	v_mov_b32_e32 v31, v0
	v_pk_mul_f32 v[32:33], v[32:33], v[32:33]
	v_add_f32_e32 v17, v28, v29
	v_pk_fma_f32 v[30:31], v[30:31], v[30:31], v[32:33]
	v_mov_b32_e32 v32, v6
	v_mov_b32_e32 v33, v2
	v_pk_fma_f32 v[30:31], v[32:33], v[32:33], v[30:31]
	v_mov_b32_e32 v32, v7
	v_mov_b32_e32 v33, v3
	v_pk_fma_f32 v[30:31], v[32:33], v[32:33], v[30:31]
	s_nop 0
	v_add_f32_e32 v17, v17, v30
	v_add_f32_e32 v17, v17, v31
	s_nop 1
	v_add_f32_dpp v17, v17, v17 quad_perm:[1,0,3,2] row_mask:0xf bank_mask:0xf
	s_nop 1
	v_add_f32_dpp v17, v17, v17 quad_perm:[2,3,0,1] row_mask:0xf bank_mask:0xf
	s_nop 1
	v_add_f32_dpp v17, v17, v17 row_half_mirror row_mask:0xf bank_mask:0xf
	s_nop 1
	v_add_f32_dpp v17, v17, v17 row_mirror row_mask:0xf bank_mask:0xf
	s_nop 1
	v_add_f32_dpp v17, v17, v17 row_bcast:15 row_mask:0xa bank_mask:0xf
	s_nop 1
	v_add_f32_dpp v17, v17, v17 row_bcast:31 row_mask:0xc bank_mask:0xf
	s_nop 1
	v_readlane_b32 vcc_lo, v17, 63
	s_nop 3
	v_mov_b32_e32 v17, vcc_lo
	v_fmamk_f32 v17, v17, 0x3a800000, v224
	v_cmp_gt_f32_e32 vcc, s12, v17
	v_mul_f32_e32 v27, 0x4b800000, v17
	s_nop 0
	v_cndmask_b32_e32 v17, v17, v27, vcc
	v_rsq_f32_e32 v17, v17
	s_nop 0
	v_mul_f32_e32 v27, 0x45800000, v17
	v_cndmask_b32_e32 v28, v17, v27, vcc
	v_pk_mul_f32 v[12:13], v[12:13], v[28:29] op_sel_hi:[1,0]
	v_pk_mul_f32 v[14:15], v[14:15], v[28:29] op_sel_hi:[1,0]
	v_pk_mul_f32 v[8:9], v[8:9], v[28:29] op_sel_hi:[1,0]
	v_pk_mul_f32 v[10:11], v[10:11], v[28:29] op_sel_hi:[1,0]
	v_pk_mul_f32 v[4:5], v[4:5], v[28:29] op_sel_hi:[1,0]
	v_pk_mul_f32 v[6:7], v[6:7], v[28:29] op_sel_hi:[1,0]
	v_pk_mul_f32 v[0:1], v[0:1], v[28:29] op_sel_hi:[1,0]
	v_pk_mul_f32 v[2:3], v[2:3], v[28:29] op_sel_hi:[1,0]
	v_pk_mul_f32 v[12:13], v[36:37], v[12:13]
	v_pk_mul_f32 v[14:15], v[38:39], v[14:15]
	v_add_co_u32_e32 v30, vcc, s20, v34
	v_cvt_pk_bf16_f32 v12, v12, v13
	v_cvt_pk_bf16_f32 v13, v14, v15
	v_addc_co_u32_e32 v31, vcc, 0, v35, vcc
	global_store_dwordx2 v[30:31], v[12:13], off offset:3072
	v_pk_mul_f32 v[8:9], v[40:41], v[8:9]
	v_pk_mul_f32 v[10:11], v[42:43], v[10:11]
	v_cvt_pk_bf16_f32 v8, v8, v9
	v_cvt_pk_bf16_f32 v9, v10, v11
	global_store_dwordx2 v[30:31], v[8:9], off offset:3584
	v_pk_mul_f32 v[4:5], v[44:45], v[4:5]
	v_pk_mul_f32 v[6:7], v[46:47], v[6:7]
	v_add_co_u32_e32 v8, vcc, s21, v34
	v_cvt_pk_bf16_f32 v4, v4, v5
	v_cvt_pk_bf16_f32 v5, v6, v7
	v_addc_co_u32_e32 v9, vcc, 0, v35, vcc
	global_store_dwordx2 v[8:9], v[4:5], off
	v_pk_mul_f32 v[0:1], v[48:49], v[0:1]
	v_pk_mul_f32 v[2:3], v[50:51], v[2:3]
	v_cvt_pk_bf16_f32 v0, v0, v1
	v_cvt_pk_bf16_f32 v1, v2, v3
	global_store_dwordx2 v[8:9], v[0:1], off offset:512
	s_andn2_saveexec_b64 s[10:11], s[10:11]
	s_cbranch_execnz .LBB0_465

; DI void phase_norm(const Params& p, const float* __restrict__ gain, bool from_input, bool zero_ssq, int tid) {
;   const int lane = tid & 63;
;   const int gw = blockIdx.x * 4 + (tid >> 6), nw = gridDim.x * 4;
;   u16* HN = (u16*)(p.ws + OFF_HN);
;   float* ssq = (float*)(p.ws + OFF_SSQ);
;   for (int g = gw; g < MPAD; g += nw) {
;     const float* xr = xrow_src(p, g, from_input);
;     u16* hr = HN + (size_t)g * 1024;
; __global__ void __launch_bounds__(256, 2) mega(Params pin) {
;     ...
;     if (ph == 0) { phase_prep(p, tid); phase_norm(p, p.attn_g, true, true, tid); continue; }
.LBB0_634:
	s_or_b64 exec, exec, s[0:1]
	v_ashrrev_i32_e32 v0, 6, v245
	v_add_u32_e32 v16, s64, v0
	v_cmp_gt_i32_e32 vcc, s93, v16
	s_and_saveexec_b64 s[0:1], vcc
	s_cbranch_execz .LBB0_6
	v_and_b32_e32 v0, 63, v245
	v_readlane_b32 s2, v254, 23
	v_lshlrev_b32_e32 v128, 4, v0
	v_readlane_b32 s3, v254, 24
	v_mul_u32_u24_e32 v1, 0x10300, v0
	v_ashrrev_i32_e32 v17, 31, v16
	v_lshl_add_u64 v[18:19], s[2:3], 0, v[128:129]
	v_lshlrev_b32_e32 v128, 2, v1
	v_lshl_add_u64 v[2:3], v[16:17], 2, v[128:129]
	s_mov_b64 s[2:3], 0x2e80800
	v_lshlrev_b64 v[22:23], 11, v[16:17]
	v_cmp_gt_u32_e64 s[4:5], 4, v0
	v_lshl_add_u64 v[20:21], v[2:3], 0, s[2:3]
	v_lshl_or_b32 v24, v0, 5, v22
	v_mov_b32_e32 v25, v23
	v_lshl_or_b32 v22, v0, 3, v22
	s_mov_b64 s[2:3], 0
	v_lshlrev_b32_e32 v26, 4, v0
	global_load_dwordx4 v[36:39], v[18:19], off
	global_load_dwordx4 v[40:43], v[18:19], off offset:1024
	global_load_dwordx4 v[44:47], v[18:19], off offset:2048
	global_load_dwordx4 v[48:51], v[18:19], off offset:3072
	s_branch .LBB0_637

; DI float4 ldgf4(const void* p) { const f32x4v v = *(const GAS f32x4v*)p; return make_float4(v.x, v.y, v.z, v.w); }
; DI void store4g(u16* dst, float a, float b, float c, float d) { u32x2 v = {pack2(a, b), pack2(c, d)}; stg8(dst, v); }
; DI void phase_norm(const Params& p, const float* __restrict__ gain, bool from_input, bool zero_ssq, int tid) {
;     ...
;   for (int g = gw; g < MPAD; g += nw) {
;     const float* xr = xrow_src(p, g, from_input);
;     u16* hr = HN + (size_t)g * 1024;
;     if (!xr) {
;       u32x4 z = {0u, 0u, 0u, 0u};
;       *(u32x4*)(hr + lane * 16) = z;
;       *(u32x4*)(hr + lane * 16 + 8) = z;
;     } else {
;       float4 v[4];
; #pragma unroll
;       for (int q = 0; q < 4; ++q) v[q] = ldgf4((const float4*)xr + lane + 64 * q);
;       float ss = 0.f;
; #pragma unroll
;       for (int q = 0; q < 4; ++q) ss += v[q].x * v[q].x + v[q].y * v[q].y + v[q].z * v[q].z + v[q].w * v[q].w;
; #pragma unroll
;       for (int o = 32; o >= 1; o >>= 1) ss += __shfl_xor(ss, o);
;       const float rstd = rsqrtf(ss * (1.0f / 1024.0f) + EPS);
; #pragma unroll
;       for (int q = 0; q < 4; ++q) {
;         const float4 gg = ldgf4((const float4*)gain + lane + 64 * q);
;         store4g(hr + 4 * (lane + 64 * q), v[q].x * rstd * gg.x, v[q].y * rstd * gg.y, v[q].z * rstd * gg.z, v[q].w * rstd * gg.w);
;       }
;     }
.LBB0_647:
	s_andn2_saveexec_b64 s[6:7], s[6:7]
	v_subrev_co_u32_e32 v128, vcc, 0x70, v3
	v_lshlrev_b64 v[0:1], 12, v[128:129]
	v_lshl_add_u64 v[0:1], s[26:27], 0, v[0:1]
	v_cndmask_b32_e64 v1, v1, 0, vcc
	v_cndmask_b32_e64 v0, v0, 0, vcc
	s_or_b64 exec, exec, s[6:7]
	v_cmp_ne_u64_e32 vcc, 0, v[0:1]
	s_and_saveexec_b64 s[6:7], vcc
	s_xor_b64 s[6:7], exec, s[6:7]
	s_cbranch_execz .LBB0_652
	v_mov_b32_e32 v27, v129
	v_lshl_add_u64 v[0:1], v[0:1], 0, v[26:27]
	global_load_dwordx4 v[12:15], v[0:1], off
	global_load_dwordx4 v[8:11], v[0:1], off offset:1024
	global_load_dwordx4 v[4:7], v[0:1], off offset:2048
	s_nop 0
	global_load_dwordx4 v[0:3], v[0:1], off offset:3072
	v_cmp_lt_i32_e32 vcc, v229, v228
	s_mov_b32 s8, 0x800000
	s_waitcnt lgkmcnt(0)
	v_lshl_add_u64 v[34:35], s[68:69], 0, v[22:23]
	v_cndmask_b32_e32 v27, v227, v229, vcc
	v_lshlrev_b32_e32 v27, 2, v27
	v_cmp_lt_i32_e32 vcc, v230, v228
	s_waitcnt vmcnt(0)
	v_mov_b32_e32 v30, v13
	v_mov_b32_e32 v31, v9
	v_mov_b32_e32 v28, v12
	v_mov_b32_e32 v29, v8
	v_pk_mul_f32 v[30:31], v[30:31], v[30:31]
	v_mov_b32_e32 v32, v5
	v_pk_fma_f32 v[28:29], v[28:29], v[28:29], v[30:31]
	v_mov_b32_e32 v30, v14
	v_mov_b32_e32 v31, v10
	v_pk_fma_f32 v[28:29], v[30:31], v[30:31], v[28:29]
	v_mov_b32_e32 v30, v15
	v_mov_b32_e32 v31, v11
	v_mov_b32_e32 v33, v1
	v_pk_fma_f32 v[28:29], v[30:31], v[30:31], v[28:29]
	v_mov_b32_e32 v30, v4
	v_mov_b32_e32 v31, v0
	v_pk_mul_f32 v[32:33], v[32:33], v[32:33]
	v_add_f32_e32 v17, v28, v29
	v_pk_fma_f32 v[30:31], v[30:31], v[30:31], v[32:33]
	v_mov_b32_e32 v32, v6
	v_mov_b32_e32 v33, v2
	v_pk_fma_f32 v[30:31], v[32:33], v[32:33], v[30:31]
	v_mov_b32_e32 v32, v7
	v_mov_b32_e32 v33, v3
	v_pk_fma_f32 v[30:31], v[32:33], v[32:33], v[30:31]
	s_nop 0
	v_add_f32_e32 v17, v17, v30
	v_add_f32_e32 v17, v17, v31
	s_nop 1
	v_add_f32_dpp v17, v17, v17 quad_perm:[1,0,3,2] row_mask:0xf bank_mask:0xf
	s_nop 1
	v_add_f32_dpp v17, v17, v17 quad_perm:[2,3,0,1] row_mask:0xf bank_mask:0xf
	s_nop 1
	v_add_f32_dpp v17, v17, v17 row_half_mirror row_mask:0xf bank_mask:0xf
	s_nop 1
	v_add_f32_dpp v17, v17, v17 row_mirror row_mask:0xf bank_mask:0xf
	s_nop 1
	v_add_f32_dpp v17, v17, v17 row_bcast:15 row_mask:0xa bank_mask:0xf
	s_nop 1
	v_add_f32_dpp v17, v17, v17 row_bcast:31 row_mask:0xc bank_mask:0xf
	s_nop 1
	v_readlane_b32 vcc_lo, v17, 63
	s_nop 3
	v_mov_b32_e32 v17, vcc_lo
	v_fmamk_f32 v17, v17, 0x3a800000, v224
	v_cmp_gt_f32_e32 vcc, s8, v17
	v_mul_f32_e32 v27, 0x4b800000, v17
	s_nop 0
	v_cndmask_b32_e32 v17, v17, v27, vcc
	v_rsq_f32_e32 v17, v17
	s_nop 0
	v_mul_f32_e32 v27, 0x45800000, v17
	v_cndmask_b32_e32 v28, v17, v27, vcc
	v_pk_mul_f32 v[12:13], v[12:13], v[28:29] op_sel_hi:[1,0]
	v_pk_mul_f32 v[14:15], v[14:15], v[28:29] op_sel_hi:[1,0]
	v_pk_mul_f32 v[8:9], v[8:9], v[28:29] op_sel_hi:[1,0]
	v_pk_mul_f32 v[10:11], v[10:11], v[28:29] op_sel_hi:[1,0]
	v_pk_mul_f32 v[4:5], v[4:5], v[28:29] op_sel_hi:[1,0]
	v_pk_mul_f32 v[6:7], v[6:7], v[28:29] op_sel_hi:[1,0]
	v_pk_mul_f32 v[0:1], v[0:1], v[28:29] op_sel_hi:[1,0]
	v_pk_mul_f32 v[2:3], v[2:3], v[28:29] op_sel_hi:[1,0]
	v_pk_mul_f32 v[12:13], v[36:37], v[12:13]
	v_pk_mul_f32 v[14:15], v[38:39], v[14:15]
	v_add_co_u32_e32 v30, vcc, s16, v34
	v_cvt_pk_bf16_f32 v12, v12, v13
	v_cvt_pk_bf16_f32 v13, v14, v15
	v_addc_co_u32_e32 v31, vcc, 0, v35, vcc
	global_store_dwordx2 v[30:31], v[12:13], off offset:3072
	v_pk_mul_f32 v[8:9], v[40:41], v[8:9]
	v_pk_mul_f32 v[10:11], v[42:43], v[10:11]
	v_cvt_pk_bf16_f32 v8, v8, v9
	v_cvt_pk_bf16_f32 v9, v10, v11
	global_store_dwordx2 v[30:31], v[8:9], off offset:3584
	v_pk_mul_f32 v[4:5], v[44:45], v[4:5]
	v_pk_mul_f32 v[6:7], v[46:47], v[6:7]
	v_add_co_u32_e32 v8, vcc, s17, v34
	v_cvt_pk_bf16_f32 v4, v4, v5
	v_cvt_pk_bf16_f32 v5, v6, v7
	v_addc_co_u32_e32 v9, vcc, 0, v35, vcc
	global_store_dwordx2 v[8:9], v[4:5], off
	v_pk_mul_f32 v[0:1], v[48:49], v[0:1]
	v_pk_mul_f32 v[2:3], v[50:51], v[2:3]
	v_cvt_pk_bf16_f32 v0, v0, v1
	v_cvt_pk_bf16_f32 v1, v2, v3
	global_store_dwordx2 v[8:9], v[0:1], off offset:512
	s_andn2_saveexec_b64 s[6:7], s[6:7]
	s_cbranch_execnz .LBB0_653
